# DSA attention K loop also 2-deep (two K-chunk gathers in flight, unrolled x2), on top of 2-deep PV loop
# baseline (speedup 1.0000x reference)
; #define DSA_GATHER(c, g_, off_) do { _Pragma("unroll") for (int i = 0; i < 8; ++i) { const unsigned kidx = ixl[(c) * 32 + kq + 4 * i]; \
;                 gr[i] = *(const u32x4*)(KV2 + ((size_t)kidx * 2 + (g_)) * 256 + (off_) + 8 * col); } } while (0)
; #define DSA_PUT() do { _Pragma("unroll") for (int i = 0; i < 8; ++i) *(LAS u32x4*)(vst + (kq + 4 * i) * 272 + col * 16) = gr[i]; } while (0)
; __device__ __forceinline__ void dsa_phase(Frame& F) {
;     ...
;             for (int g = 0; g < 2; ++g) {
;                 bf16x8 qf[4];
; #pragma unroll
;                 for (int ks = 0; ks < 4; ++ks) { if (col < 4) qf[ks] = *(const bf16x8*)(U + (size_t)t * PWP + UQ + 128 * (4 * g + col) + 32 * ks + 8 * kq); else qf[ks] = (bf16x8){0, 0, 0, 0, 0, 0, 0, 0}; }
;                 DSA_GATHER(0, g, 0);
;                 for (int c = 0; c < nch; ++c) {
;                     DSA_PUT();
;                     if (c + 1 < nch) DSA_GATHER(c + 1, g, 0); else DSA_GATHER(0, g, 128);
.LBB0_1157:
	s_or_b64 exec, exec, s[18:19]
	v_add_u32_e32 v0, s29, v206
	ds_read_u16 v1, v0 offset:10240
	ds_read_u16 v2, v0 offset:10248
	s_waitcnt lgkmcnt(2)
	ds_read_u16 v8, v0 offset:10256
	ds_read_u16 v10, v0 offset:10264
	ds_read_u16 v16, v0 offset:10272
	ds_read_u16 v18, v0 offset:10280
	ds_read_u16 v24, v0 offset:10288
	ds_read_u16 v26, v0 offset:10296
	v_lshl_add_u64 v[52:53], v[146:147], 0, s[52:53]
	s_waitcnt lgkmcnt(7)
	v_lshlrev_b32_e32 v138, 10, v1
	s_waitcnt lgkmcnt(6)
	v_lshlrev_b32_e32 v48, 10, v2
	v_mov_b32_e32 v49, v139
	s_waitcnt lgkmcnt(5)
	v_lshlrev_b32_e32 v50, 10, v8
	v_mov_b32_e32 v51, v139
	s_waitcnt lgkmcnt(4)
	v_lshlrev_b32_e32 v60, 10, v10
	v_mov_b32_e32 v61, v139
	s_waitcnt lgkmcnt(3)
	v_lshlrev_b32_e32 v62, 10, v16
	v_mov_b32_e32 v63, v139
	s_waitcnt lgkmcnt(2)
	v_lshlrev_b32_e32 v66, 10, v18
	v_mov_b32_e32 v67, v139
	s_waitcnt lgkmcnt(1)
	v_lshlrev_b32_e32 v72, 10, v24
	v_mov_b32_e32 v73, v139
	s_waitcnt lgkmcnt(0)
	v_lshlrev_b32_e32 v74, 10, v26
	v_mov_b32_e32 v75, v139
	v_lshl_add_u64 v[0:1], v[52:53], 0, v[138:139]
	v_lshl_add_u64 v[4:5], v[52:53], 0, v[48:49]
	v_lshl_add_u64 v[8:9], v[52:53], 0, v[50:51]
	v_lshl_add_u64 v[12:13], v[52:53], 0, v[60:61]
	v_lshl_add_u64 v[16:17], v[52:53], 0, v[62:63]
	v_lshl_add_u64 v[20:21], v[52:53], 0, v[66:67]
	v_lshl_add_u64 v[24:25], v[52:53], 0, v[72:73]
	v_lshl_add_u64 v[28:29], v[52:53], 0, v[74:75]
	global_load_dwordx4 v[0:3], v[0:1], off
	s_nop 0
	global_load_dwordx4 v[4:7], v[4:5], off
	s_nop 0
	global_load_dwordx4 v[8:11], v[8:9], off
	s_nop 0
	global_load_dwordx4 v[12:15], v[12:13], off
	s_nop 0
	global_load_dwordx4 v[16:19], v[16:17], off
	s_nop 0
	global_load_dwordx4 v[20:23], v[20:21], off
	s_nop 0
	global_load_dwordx4 v[24:27], v[24:25], off
	s_nop 0
	global_load_dwordx4 v[28:31], v[28:29], off
	v_cndmask_b32_e64 v54, 0, 1, s[22:23]
	s_lshl_b32 s65, s65, 8
	v_cmp_ne_u32_e64 s[18:19], 1, v54
	s_andn2_b64 vcc, exec, s[22:23]
	v_lshlrev_b32_e32 v64, 1, v144
	s_cbranch_vccnz .LBB0_1166
	s_lshl_b32 s24, s65, 1
	s_add_u32 s24, s48, s24
	s_addc_u32 s25, s49, 0
	v_mov_b32_e32 v65, v139
	v_lshl_add_u64 v[48:49], s[24:25], 0, v[48:49]
	v_lshl_add_u64 v[48:49], v[48:49], 0, v[64:65]
	v_lshl_add_u64 v[56:57], v[48:49], 0, s[62:63]
	v_lshl_add_u64 v[48:49], s[24:25], 0, v[50:51]
	v_lshl_add_u64 v[48:49], v[48:49], 0, v[64:65]
	v_lshl_add_u64 v[58:59], v[48:49], 0, s[62:63]
	v_lshl_add_u64 v[48:49], s[24:25], 0, v[60:61]
	v_lshl_add_u64 v[48:49], v[48:49], 0, v[64:65]
	v_lshl_add_u64 v[60:61], v[48:49], 0, s[62:63]
	v_lshl_add_u64 v[48:49], s[24:25], 0, v[62:63]
	v_lshl_add_u64 v[48:49], v[48:49], 0, v[64:65]
	v_lshl_add_u64 v[62:63], v[48:49], 0, s[62:63]
	v_lshl_add_u64 v[48:49], s[24:25], 0, v[66:67]
	v_lshl_add_u64 v[48:49], v[48:49], 0, v[64:65]
	v_lshl_add_u64 v[66:67], v[48:49], 0, s[62:63]
	v_lshl_add_u64 v[48:49], s[24:25], 0, v[72:73]
	v_lshl_add_u64 v[48:49], v[48:49], 0, v[64:65]
	v_lshl_add_u64 v[54:55], s[24:25], 0, v[138:139]
	v_lshl_add_u64 v[72:73], v[48:49], 0, s[62:63]
	v_lshl_add_u64 v[48:49], s[24:25], 0, v[74:75]
	v_lshl_add_u64 v[54:55], v[54:55], 0, v[64:65]
	v_lshl_add_u64 v[48:49], v[48:49], 0, v[64:65]
	v_lshl_add_u64 v[54:55], v[54:55], 0, s[62:63]
	v_lshl_add_u64 v[74:75], v[48:49], 0, s[62:63]
	s_mov_b32 s66, 0
	v_mov_b32_e32 v65, v76
	v_mov_b32_e32 v77, v208
	s_cmp_gt_i32 s64, 1
	s_cbranch_scc0 .Lk_A
	ds_read_u16 v95, v76
	ds_read_u16 v96, v76 offset:8
	ds_read_u16 v102, v76 offset:16
	ds_read_u16 v104, v76 offset:24
	ds_read_u16 v110, v76 offset:32
	ds_read_u16 v112, v76 offset:40
	ds_read_u16 v118, v76 offset:48
	ds_read_u16 v120, v76 offset:56
	s_waitcnt lgkmcnt(7)
	v_lshlrev_b32_e32 v138, 10, v95
	v_lshl_add_u64 v[94:95], v[52:53], 0, v[138:139]
	s_waitcnt lgkmcnt(6)
	v_lshlrev_b32_e32 v138, 10, v96
	v_lshl_add_u64 v[98:99], v[52:53], 0, v[138:139]
	s_waitcnt lgkmcnt(5)
	v_lshlrev_b32_e32 v138, 10, v102
	v_lshl_add_u64 v[102:103], v[52:53], 0, v[138:139]
	s_waitcnt lgkmcnt(4)
	v_lshlrev_b32_e32 v138, 10, v104
	v_lshl_add_u64 v[106:107], v[52:53], 0, v[138:139]
	s_waitcnt lgkmcnt(3)
	v_lshlrev_b32_e32 v138, 10, v110
	v_lshl_add_u64 v[110:111], v[52:53], 0, v[138:139]
	s_waitcnt lgkmcnt(2)
	v_lshlrev_b32_e32 v138, 10, v112
	v_lshl_add_u64 v[114:115], v[52:53], 0, v[138:139]
	s_waitcnt lgkmcnt(1)
	v_lshlrev_b32_e32 v138, 10, v118
	v_lshl_add_u64 v[118:119], v[52:53], 0, v[138:139]
	s_waitcnt lgkmcnt(0)
	v_lshlrev_b32_e32 v138, 10, v120
	v_lshl_add_u64 v[122:123], v[52:53], 0, v[138:139]
	global_load_dwordx4 v[94:97], v[94:95], off
	s_nop 0
	global_load_dwordx4 v[98:101], v[98:99], off
	s_nop 0
	global_load_dwordx4 v[102:105], v[102:103], off
	s_nop 0
	global_load_dwordx4 v[106:109], v[106:107], off
	s_nop 0
	global_load_dwordx4 v[110:113], v[110:111], off
	s_nop 0
	global_load_dwordx4 v[114:117], v[114:115], off
	s_nop 0
	global_load_dwordx4 v[118:121], v[118:119], off
	s_nop 0
	global_load_dwordx4 v[122:125], v[122:123], off
; #define LAS __attribute__((address_space(3)))
; #define DSA_GATHER(c, g_, off_) do { _Pragma("unroll") for (int i = 0; i < 8; ++i) { const unsigned kidx = ixl[(c) * 32 + kq + 4 * i]; \
;                 gr[i] = *(const u32x4*)(KV2 + ((size_t)kidx * 2 + (g_)) * 256 + (off_) + 8 * col); } } while (0)
; #define DSA_PUT() do { _Pragma("unroll") for (int i = 0; i < 8; ++i) *(LAS u32x4*)(vst + (kq + 4 * i) * 272 + col * 16) = gr[i]; } while (0)
; __device__ __forceinline__ void dsa_phase(Frame& F) {
;     ...
;                 for (int c = 0; c < nch; ++c) {
;                     DSA_PUT();
;                     if (c + 1 < nch) DSA_GATHER(c + 1, g, 0); else DSA_GATHER(0, g, 128);
; #pragma unroll
;                     for (int kb2 = 0; kb2 < 2; ++kb2) {
;                         f32x4 a4 = {0.f, 0.f, 0.f, 0.f};
; #pragma unroll
;                         for (int ks = 0; ks < 4; ++ks) { const bf16x8 kf = *(const LAS bf16x8*)(vst + (16 * kb2 + col) * 272 + (32 * ks + 8 * kq) * 2); a4 = __builtin_amdgcn_mfma_f32_16x16x32_bf16(kf, qf[ks], a4, 0, 0, 0); }
;                         if (col < 4) {
; #pragma unroll
;                             for (int i = 0; i < 4; ++i) Pw[(32 * c + 16 * kb2 + 4 * kq + i) * 4 + col] = a4[i] * 0.08838834764831845f;
.Lk_A:
	s_nop 0
	v_add_u32_e32 v48, v205, v207
	s_add_i32 s66, s66, 1
	s_cmp_lt_i32 s66, s64
	s_cbranch_scc0 .Lk_A_last
	s_waitcnt vmcnt(15)
	ds_write_b128 v48, v[0:3]
	s_waitcnt vmcnt(14)
	ds_write_b128 v48, v[4:7] offset:1088
	s_waitcnt vmcnt(13)
	ds_write_b128 v48, v[8:11] offset:2176
	s_waitcnt vmcnt(12)
	ds_write_b128 v48, v[12:15] offset:3264
	s_waitcnt vmcnt(11)
	ds_write_b128 v48, v[16:19] offset:4352
	s_waitcnt vmcnt(10)
	ds_write_b128 v48, v[20:23] offset:5440
	s_waitcnt vmcnt(9)
	ds_write_b128 v48, v[24:27] offset:6528
	s_waitcnt vmcnt(8)
	ds_write_b128 v48, v[28:31] offset:7616
	s_add_i32 s24, s66, 1
	s_cmp_lt_i32 s24, s64
	s_cbranch_scc0 .Lk_A_c
	ds_read_u16 v1, v65 offset:64
	ds_read_u16 v2, v65 offset:72
	ds_read_u16 v8, v65 offset:80
	ds_read_u16 v10, v65 offset:88
	ds_read_u16 v16, v65 offset:96
	ds_read_u16 v18, v65 offset:104
	ds_read_u16 v24, v65 offset:112
	ds_read_u16 v26, v65 offset:120
	s_waitcnt lgkmcnt(7)
	v_lshlrev_b32_e32 v138, 10, v1
	v_lshl_add_u64 v[0:1], v[52:53], 0, v[138:139]
	s_waitcnt lgkmcnt(6)
	v_lshlrev_b32_e32 v138, 10, v2
	v_lshl_add_u64 v[4:5], v[52:53], 0, v[138:139]
	s_waitcnt lgkmcnt(5)
	v_lshlrev_b32_e32 v138, 10, v8
	v_lshl_add_u64 v[8:9], v[52:53], 0, v[138:139]
	s_waitcnt lgkmcnt(4)
	v_lshlrev_b32_e32 v138, 10, v10
	v_lshl_add_u64 v[12:13], v[52:53], 0, v[138:139]
	s_waitcnt lgkmcnt(3)
	v_lshlrev_b32_e32 v138, 10, v16
	v_lshl_add_u64 v[16:17], v[52:53], 0, v[138:139]
	s_waitcnt lgkmcnt(2)
	v_lshlrev_b32_e32 v138, 10, v18
	v_lshl_add_u64 v[20:21], v[52:53], 0, v[138:139]
	s_waitcnt lgkmcnt(1)
	v_lshlrev_b32_e32 v138, 10, v24
	v_lshl_add_u64 v[24:25], v[52:53], 0, v[138:139]
	s_waitcnt lgkmcnt(0)
	v_lshlrev_b32_e32 v138, 10, v26
	v_lshl_add_u64 v[28:29], v[52:53], 0, v[138:139]
	global_load_dwordx4 v[0:3], v[0:1], off
	s_nop 0
	global_load_dwordx4 v[4:7], v[4:5], off
	s_nop 0
	global_load_dwordx4 v[8:11], v[8:9], off
	s_nop 0
	global_load_dwordx4 v[12:15], v[12:13], off
	s_nop 0
	global_load_dwordx4 v[16:19], v[16:17], off
	s_nop 0
	global_load_dwordx4 v[20:23], v[20:21], off
	s_nop 0
	global_load_dwordx4 v[24:27], v[24:25], off
	s_nop 0
	global_load_dwordx4 v[28:31], v[28:29], off
	s_branch .Lk_A_c
.Lk_A_last:
	s_waitcnt vmcnt(7)
	ds_write_b128 v48, v[0:3]
	s_waitcnt vmcnt(6)
	ds_write_b128 v48, v[4:7] offset:1088
	s_waitcnt vmcnt(5)
	ds_write_b128 v48, v[8:11] offset:2176
	s_waitcnt vmcnt(4)
	ds_write_b128 v48, v[12:15] offset:3264
	s_waitcnt vmcnt(3)
	ds_write_b128 v48, v[16:19] offset:4352
	s_waitcnt vmcnt(2)
	ds_write_b128 v48, v[20:23] offset:5440
	s_waitcnt vmcnt(1)
	ds_write_b128 v48, v[24:27] offset:6528
	s_waitcnt vmcnt(0)
	ds_write_b128 v48, v[28:31] offset:7616
	global_load_dwordx4 v[0:3], v[54:55], off
	global_load_dwordx4 v[4:7], v[56:57], off
	global_load_dwordx4 v[8:11], v[58:59], off
	global_load_dwordx4 v[12:15], v[60:61], off
	global_load_dwordx4 v[16:19], v[62:63], off
	global_load_dwordx4 v[20:23], v[66:67], off
	global_load_dwordx4 v[24:27], v[72:73], off
	global_load_dwordx4 v[28:31], v[74:75], off
.Lk_A_c:
	ds_read_b128 v[48:51], v215
	ds_read_b128 v[78:81], v215 offset:64
	ds_read_b128 v[82:85], v215 offset:128
	s_waitcnt lgkmcnt(2)
	v_mfma_f32_16x16x32_bf16 v[48:51], v[48:51], v[36:39], 0
	s_waitcnt lgkmcnt(1)
	v_mfma_f32_16x16x32_bf16 v[48:51], v[78:81], v[32:35], v[48:51]
	ds_read_b128 v[78:81], v215 offset:192
	s_waitcnt lgkmcnt(1)
	v_mfma_f32_16x16x32_bf16 v[48:51], v[82:85], v[44:47], v[48:51]
	s_waitcnt lgkmcnt(0)
	v_mfma_f32_16x16x32_bf16 v[48:51], v[78:81], v[40:43], v[48:51]
	s_and_saveexec_b64 s[24:25], s[8:9]
	s_cbranch_execz .Lk_A_m
	s_nop 5
	v_mul_f32_e32 v49, 0x3db504f3, v49
	v_mul_f32_e32 v48, 0x3db504f3, v48
	v_mul_f32_e32 v51, 0x3db504f3, v51
	v_mul_f32_e32 v50, 0x3db504f3, v50
	ds_write2_b32 v77, v48, v49 offset1:4
	ds_write2_b32 v77, v50, v51 offset0:8 offset1:12
; #define LAS __attribute__((address_space(3)))
; __device__ __forceinline__ void dsa_phase(Frame& F) {
;     ...
;                     for (int kb2 = 0; kb2 < 2; ++kb2) {
;                         f32x4 a4 = {0.f, 0.f, 0.f, 0.f};
; #pragma unroll
;                         for (int ks = 0; ks < 4; ++ks) { const bf16x8 kf = *(const LAS bf16x8*)(vst + (16 * kb2 + col) * 272 + (32 * ks + 8 * kq) * 2); a4 = __builtin_amdgcn_mfma_f32_16x16x32_bf16(kf, qf[ks], a4, 0, 0, 0); }
;                         if (col < 4) {
; #pragma unroll
;                             for (int i = 0; i < 4; ++i) Pw[(32 * c + 16 * kb2 + 4 * kq + i) * 4 + col] = a4[i] * 0.08838834764831845f;
;                         }
;                     }
.Lk_A_m:
	s_or_b64 exec, exec, s[24:25]
	s_nop 4
	ds_read_b128 v[48:51], v215 offset:4352
	ds_read_b128 v[78:81], v215 offset:4416
	ds_read_b128 v[82:85], v215 offset:4480
	s_waitcnt lgkmcnt(2)
	v_mfma_f32_16x16x32_bf16 v[48:51], v[48:51], v[36:39], 0
	s_waitcnt lgkmcnt(1)
	v_mfma_f32_16x16x32_bf16 v[48:51], v[78:81], v[32:35], v[48:51]
	ds_read_b128 v[78:81], v215 offset:4544
	s_waitcnt lgkmcnt(1)
	v_mfma_f32_16x16x32_bf16 v[48:51], v[82:85], v[44:47], v[48:51]
	s_waitcnt lgkmcnt(0)
	v_mfma_f32_16x16x32_bf16 v[48:51], v[78:81], v[40:43], v[48:51]
	s_and_saveexec_b64 s[24:25], s[8:9]
	s_cbranch_execz .Lk_A_l
	s_nop 5
	v_mul_f32_e32 v49, 0x3db504f3, v49
	v_mul_f32_e32 v48, 0x3db504f3, v48
	v_mul_f32_e32 v51, 0x3db504f3, v51
	v_mul_f32_e32 v50, 0x3db504f3, v50
	ds_write2_b32 v77, v48, v49 offset0:64 offset1:68
	ds_write2_b32 v77, v50, v51 offset0:72 offset1:76
.Lk_A_l:
	s_or_b64 exec, exec, s[24:25]
	v_add_u32_e32 v77, 0x200, v77
	s_cmp_eq_u32 s64, s66
	v_add_u32_e32 v65, 64, v65
	s_cbranch_scc1 .LBB0_1166
.Lk_B:
	s_nop 0
	v_add_u32_e32 v48, v205, v207
	s_add_i32 s66, s66, 1
	s_cmp_lt_i32 s66, s64
	s_cbranch_scc0 .Lk_B_last
	s_waitcnt vmcnt(15)
	ds_write_b128 v48, v[94:97]
	s_waitcnt vmcnt(14)
	ds_write_b128 v48, v[98:101] offset:1088
	s_waitcnt vmcnt(13)
	ds_write_b128 v48, v[102:105] offset:2176
	s_waitcnt vmcnt(12)
	ds_write_b128 v48, v[106:109] offset:3264
	s_waitcnt vmcnt(11)
	ds_write_b128 v48, v[110:113] offset:4352
	s_waitcnt vmcnt(10)
	ds_write_b128 v48, v[114:117] offset:5440
	s_waitcnt vmcnt(9)
	ds_write_b128 v48, v[118:121] offset:6528
	s_waitcnt vmcnt(8)
	ds_write_b128 v48, v[122:125] offset:7616
	s_add_i32 s24, s66, 1
	s_cmp_lt_i32 s24, s64
	s_cbranch_scc0 .Lk_B_c
	ds_read_u16 v95, v65 offset:64
	ds_read_u16 v96, v65 offset:72
	ds_read_u16 v102, v65 offset:80
	ds_read_u16 v104, v65 offset:88
	ds_read_u16 v110, v65 offset:96
	ds_read_u16 v112, v65 offset:104
	ds_read_u16 v118, v65 offset:112
	ds_read_u16 v120, v65 offset:120
	s_waitcnt lgkmcnt(7)
	v_lshlrev_b32_e32 v138, 10, v95
	v_lshl_add_u64 v[94:95], v[52:53], 0, v[138:139]
	s_waitcnt lgkmcnt(6)
	v_lshlrev_b32_e32 v138, 10, v96
	v_lshl_add_u64 v[98:99], v[52:53], 0, v[138:139]
	s_waitcnt lgkmcnt(5)
	v_lshlrev_b32_e32 v138, 10, v102
	v_lshl_add_u64 v[102:103], v[52:53], 0, v[138:139]
	s_waitcnt lgkmcnt(4)
	v_lshlrev_b32_e32 v138, 10, v104
	v_lshl_add_u64 v[106:107], v[52:53], 0, v[138:139]
	s_waitcnt lgkmcnt(3)
	v_lshlrev_b32_e32 v138, 10, v110
	v_lshl_add_u64 v[110:111], v[52:53], 0, v[138:139]
	s_waitcnt lgkmcnt(2)
	v_lshlrev_b32_e32 v138, 10, v112
	v_lshl_add_u64 v[114:115], v[52:53], 0, v[138:139]
	s_waitcnt lgkmcnt(1)
	v_lshlrev_b32_e32 v138, 10, v118
	v_lshl_add_u64 v[118:119], v[52:53], 0, v[138:139]
	s_waitcnt lgkmcnt(0)
	v_lshlrev_b32_e32 v138, 10, v120
	v_lshl_add_u64 v[122:123], v[52:53], 0, v[138:139]
	global_load_dwordx4 v[94:97], v[94:95], off
	s_nop 0
	global_load_dwordx4 v[98:101], v[98:99], off
	s_nop 0
	global_load_dwordx4 v[102:105], v[102:103], off
	s_nop 0
	global_load_dwordx4 v[106:109], v[106:107], off
	s_nop 0
	global_load_dwordx4 v[110:113], v[110:111], off
	s_nop 0
	global_load_dwordx4 v[114:117], v[114:115], off
	s_nop 0
	global_load_dwordx4 v[118:121], v[118:119], off
	s_nop 0
	global_load_dwordx4 v[122:125], v[122:123], off
	s_branch .Lk_B_c
.Lk_B_last:
	s_waitcnt vmcnt(7)
	ds_write_b128 v48, v[94:97]
	s_waitcnt vmcnt(6)
	ds_write_b128 v48, v[98:101] offset:1088
	s_waitcnt vmcnt(5)
	ds_write_b128 v48, v[102:105] offset:2176
	s_waitcnt vmcnt(4)
	ds_write_b128 v48, v[106:109] offset:3264
	s_waitcnt vmcnt(3)
	ds_write_b128 v48, v[110:113] offset:4352
	s_waitcnt vmcnt(2)
	ds_write_b128 v48, v[114:117] offset:5440
	s_waitcnt vmcnt(1)
	ds_write_b128 v48, v[118:121] offset:6528
	s_waitcnt vmcnt(0)
	ds_write_b128 v48, v[122:125] offset:7616
	global_load_dwordx4 v[0:3], v[54:55], off
	global_load_dwordx4 v[4:7], v[56:57], off
	global_load_dwordx4 v[8:11], v[58:59], off
	global_load_dwordx4 v[12:15], v[60:61], off
	global_load_dwordx4 v[16:19], v[62:63], off
	global_load_dwordx4 v[20:23], v[66:67], off
	global_load_dwordx4 v[24:27], v[72:73], off
	global_load_dwordx4 v[28:31], v[74:75], off

; #define DSA_GATHER(c, g_, off_) do { _Pragma("unroll") for (int i = 0; i < 8; ++i) { const unsigned kidx = ixl[(c) * 32 + kq + 4 * i]; \
;                 gr[i] = *(const u32x4*)(KV2 + ((size_t)kidx * 2 + (g_)) * 256 + (off_) + 8 * col); } } while (0)
; #define DSA_PUT() do { _Pragma("unroll") for (int i = 0; i < 8; ++i) *(LAS u32x4*)(vst + (kq + 4 * i) * 272 + col * 16) = gr[i]; } while (0)
; __device__ __forceinline__ void dsa_phase(Frame& F) {
;     ...
;                 for (int c = 0; c < nch; ++c) {
;                     DSA_PUT();
;                     if (c + 1 < nch) DSA_GATHER(c + 1, g, 0); else DSA_GATHER(0, g, 128);
.Lk_B_l:
	s_or_b64 exec, exec, s[24:25]
	v_add_u32_e32 v77, 0x200, v77
	s_cmp_eq_u32 s64, s66
	v_add_u32_e32 v65, 64, v65
	s_cbranch_scc1 .LBB0_1166
	s_branch .Lk_A
